# out-proj K loop: LDS-DMA issued from SGPR tile bases + 32-bit per-lane offsets right after the barrier (hipcc's 64-bit per-lane address arithmetic removed)
# speedup vs baseline: 1.0187x; 1.0022x over previous
.LBB0_74:
	s_and_b32 s10, s8, 0xffffe00
	v_readlane_b32 s13, v253, 45
	s_or_b32 s10, s13, s10
	s_and_b32 s12, s9, 56
	s_add_i32 s10, s10, s12
	s_lshl_b32 s10, s10, 4
	v_mov_b32_e32 v8, v151
	s_ashr_i32 s11, s10, 31
	s_lshl_b64 s[40:41], s[10:11], 1
	v_bfe_u32 v12, v8, 4, 2
	s_and_b32 s10, s7, 7
	v_and_b32_e32 v9, 63, v8
	v_ashrrev_i32_e32 v11, 6, v8
	v_xor_b32_e32 v0, v12, v8
	s_lshl_b32 s11, s10, 18
	s_lshl_b32 s10, s9, 3
	v_lshl_or_b32 v3, v11, 8, v9
	v_lshlrev_b32_e32 v0, 3, v0
	s_and_b32 s10, s10, 0xfffffe00
	s_or_b32 s12, s12, s13
	v_lshlrev_b32_e32 v2, 7, v3
	v_and_b32_e32 v13, 56, v0
	s_movk_i32 s42, 0x9c00
	s_or_b32 s10, s12, s10
	v_and_or_b32 v0, v2, s42, v13
	v_or_b32_e32 v2, 64, v3
	s_ashr_i32 s12, s10, 3
	v_lshrrev_b32_e32 v4, 4, v2
	s_ashr_i32 s13, s12, 31
	v_xor_b32_e32 v4, v4, v8
	v_or_b32_e32 v3, 0xc0, v3
	s_and_b32 s10, s9, 7
	s_lshl_b64 s[28:29], s[12:13], 17
	s_lshl_b64 s[38:39], s[12:13], 18
	v_lshlrev_b32_e32 v14, 7, v2
	v_lshlrev_b32_e32 v2, 3, v4
	v_lshrrev_b32_e32 v4, 4, v3
	s_add_u32 s12, s94, s38
	v_xor_b32_e32 v4, v4, v8
	v_lshlrev_b32_e32 v122, 12, v11
	s_addc_u32 s13, s95, s39
	s_lshl_b32 s14, s10, 18
	v_lshlrev_b32_e32 v16, 7, v3
	v_lshlrev_b32_e32 v3, 3, v4
	v_lshlrev_b64 v[4:5], 1, v[0:1]
	v_readfirstlane_b32 s16, v122
	v_add_u32_e32 v123, 0x4000, v122
	s_add_u32 s14, s5, s14
	v_lshl_add_u64 v[6:7], s[12:13], 0, v[4:5]
	s_mov_b32 m0, s16
	v_readfirstlane_b32 s16, v123
	s_addc_u32 s15, s6, 0
	v_and_b32_e32 v15, 56, v2
	s_mov_b64 s[48:49], s[12:13]
	s_mov_b64 s[100:101], s[14:15]
	v_and_b32_e32 v250, 63, v151
	v_lshrrev_b32_e32 v251, 4, v250
	v_and_b32_e32 v185, 7, v250
	v_xor_b32_e32 v185, v185, v251
	v_lshlrev_b32_e32 v185, 4, v185
	v_lshrrev_b32_e32 v251, 3, v250
	v_lshl_or_b32 v185, v251, 11, v185
	v_lshrrev_b32_e32 v251, 6, v151
	v_lshl_add_u32 v185, v251, 16, v185
	v_add_u32_e32 v185, 0x80, v185
	v_xor_b32_e32 v188, 64, v185
	v_add_u32_e32 v188, 0x4000, v188
	v_add_u32_e32 v193, 0x8000, v185
	v_add_u32_e32 v194, 0x8000, v188
	s_barrier
	global_load_lds_dwordx4 v[6:7], off
	s_mov_b32 m0, s16
	s_movk_i32 s16, 0xbc00
	v_or_b32_e32 v2, 0x4000, v0
	v_lshl_add_u64 v[4:5], s[14:15], 0, v[4:5]
	v_and_or_b32 v0, v14, s16, v15
	global_load_lds_dwordx4 v[4:5], off
	v_lshlrev_b64 v[4:5], 1, v[0:1]
	v_or_b32_e32 v0, 0x400, v122
	v_add_u32_e32 v124, 0x4400, v122
	v_readfirstlane_b32 s16, v0
	v_and_b32_e32 v17, 56, v3
	v_lshl_add_u64 v[6:7], s[12:13], 0, v[4:5]
	s_mov_b32 m0, s16
	v_readfirstlane_b32 s16, v124
	v_mov_b32_e32 v3, v1
	v_or_b32_e32 v0, 0x800, v122
	global_load_lds_dwordx4 v[6:7], off
	v_lshl_add_u64 v[6:7], s[14:15], 0, v[4:5]
	s_mov_b32 m0, s16
	v_lshlrev_b64 v[2:3], 1, v[2:3]
	v_readfirstlane_b32 s16, v0
	v_add_u32_e32 v125, 0x4800, v122
	global_load_lds_dwordx4 v[6:7], off
	v_lshl_add_u64 v[6:7], s[12:13], 0, v[2:3]
	s_mov_b32 m0, s16
	v_readfirstlane_b32 s16, v125
	global_load_lds_dwordx4 v[6:7], off
	s_mov_b32 m0, s16
	v_readlane_b32 s16, v255, 35
	v_readlane_b32 s17, v255, 36
	s_movk_i32 s17, 0xfc00
	v_lshl_add_u64 v[2:3], s[14:15], 0, v[2:3]
	v_and_or_b32 v0, v16, s17, v17
	global_load_lds_dwordx4 v[2:3], off
	v_lshlrev_b64 v[2:3], 1, v[0:1]
	v_or_b32_e32 v0, 0xc00, v122
	v_lshl_add_u64 v[6:7], s[12:13], 0, v[2:3]
	v_readfirstlane_b32 s12, v0
	v_add_u32_e32 v126, 0x4c00, v122
	s_mov_b32 m0, s12
	v_readfirstlane_b32 s12, v126
	global_load_lds_dwordx4 v[6:7], off
	v_lshl_add_u64 v[6:7], s[14:15], 0, v[2:3]
	s_mov_b32 m0, s12
	v_lshrrev_b32_e32 v0, 1, v8
	global_load_lds_dwordx4 v[6:7], off
	v_ashrrev_i32_e32 v10, 7, v8
	v_bitop3_b32 v0, v12, v0, 7 bitop3:0x78
	v_lshlrev_b32_e32 v16, 13, v11
	v_bfe_u32 v6, v8, 1, 3
	v_lshlrev_b32_e32 v0, 4, v0
	v_lshlrev_b32_e32 v7, 13, v10
	v_and_b32_e32 v16, 0x2000, v16
	v_or_b32_e32 v15, v0, v7
	v_or_b32_e32 v17, v0, v16
	v_bitop3_b32 v0, v12, v6, 4 bitop3:0x36
	v_lshlrev_b32_e32 v6, 3, v8
	v_lshlrev_b32_e32 v0, 4, v0
	v_and_b32_e32 v6, 0x78, v6
	v_or_b32_e32 v12, v0, v7
	v_add_u32_e32 v7, 0x100, v8
	s_waitcnt vmcnt(0)
	v_lshlrev_b32_e32 v24, 7, v6
	v_or_b32_e32 v27, 2, v6
	v_or_b32_e32 v30, 3, v6
	v_or_b32_e32 v33, 4, v6
	v_or_b32_e32 v36, 5, v6
	v_or_b32_e32 v39, 6, v6
	v_or_b32_e32 v6, 7, v6
	v_ashrrev_i32_e32 v18, 4, v7
	v_lshlrev_b32_e32 v25, 2, v8
	v_lshlrev_b32_e32 v28, 7, v27
	v_lshrrev_b32_e32 v27, 1, v27
	v_lshlrev_b32_e32 v31, 7, v30
	v_lshrrev_b32_e32 v30, 1, v30
	v_lshlrev_b32_e32 v34, 7, v33
	v_lshrrev_b32_e32 v33, 1, v33
	v_lshlrev_b32_e32 v37, 7, v36
	v_lshrrev_b32_e32 v36, 1, v36
	v_lshlrev_b32_e32 v40, 7, v39
	v_lshrrev_b32_e32 v39, 1, v39
	v_lshlrev_b32_e32 v42, 7, v6
	v_lshrrev_b32_e32 v6, 1, v6
	v_ashrrev_i32_e32 v7, 7, v7
	v_add_u32_e32 v19, 0x200, v8
	v_bitop3_b32 v43, v25, v7, 4 bitop3:0x6c
	v_bitop3_b32 v44, v27, v7, 5 bitop3:0x6c
	v_bitop3_b32 v45, v30, v7, 5 bitop3:0x6c
	v_bitop3_b32 v46, v33, v7, 6 bitop3:0x6c
	v_bitop3_b32 v47, v36, v7, 6 bitop3:0x6c
	v_bitop3_b32 v48, v39, v7, 7 bitop3:0x6c
	v_bitop3_b32 v7, v6, v7, 7 bitop3:0x6c
	v_lshl_add_u32 v49, v7, 4, v42
	v_ashrrev_i32_e32 v7, 7, v19
	v_ashrrev_i32_e32 v20, 4, v19
	v_add_u32_e32 v21, 0x300, v8
	v_bitop3_b32 v19, v25, v7, 4 bitop3:0x6c
	v_bitop3_b32 v50, v27, v7, 5 bitop3:0x6c
	v_bitop3_b32 v51, v30, v7, 5 bitop3:0x6c
	v_bitop3_b32 v52, v33, v7, 6 bitop3:0x6c
	v_bitop3_b32 v53, v36, v7, 6 bitop3:0x6c
	v_bitop3_b32 v54, v39, v7, 7 bitop3:0x6c
	v_bitop3_b32 v7, v6, v7, 7 bitop3:0x6c
	v_lshl_add_u32 v55, v7, 4, v42
	v_ashrrev_i32_e32 v7, 7, v21
	v_ashrrev_i32_e32 v22, 4, v21
	v_bitop3_b32 v26, v25, v10, 4 bitop3:0x6c
	v_bitop3_b32 v21, v25, v7, 4 bitop3:0x6c
	v_lshlrev_b32_e32 v14, 7, v8
	v_or_b32_e32 v16, v0, v16
	v_ashrrev_i32_e32 v0, 4, v8
	v_lshrrev_b32_e32 v23, 3, v8
	v_lshl_add_u32 v26, v26, 4, v24
	v_bitop3_b32 v29, v27, v10, 5 bitop3:0x6c
	v_bitop3_b32 v32, v30, v10, 5 bitop3:0x6c
	v_bitop3_b32 v35, v33, v10, 6 bitop3:0x6c
	v_bitop3_b32 v38, v36, v10, 6 bitop3:0x6c
	v_bitop3_b32 v41, v39, v10, 7 bitop3:0x6c
	v_bitop3_b32 v10, v6, v10, 7 bitop3:0x6c
	v_lshl_add_u32 v43, v43, 4, v24
	v_lshl_add_u32 v19, v19, 4, v24
	v_lshl_add_u32 v21, v21, 4, v24
	v_bitop3_b32 v24, v27, v7, 5 bitop3:0x6c
	v_bitop3_b32 v25, v30, v7, 5 bitop3:0x6c
	v_bitop3_b32 v6, v6, v7, 7 bitop3:0x6c
	s_mov_b32 s14, 0xc000
	v_lshlrev_b32_e32 v8, 4, v8
	v_lshl_add_u32 v29, v29, 4, v28
	v_lshl_add_u32 v32, v32, 4, v31
	v_lshl_add_u32 v44, v44, 4, v28
	v_lshl_add_u32 v45, v45, 4, v31
	v_lshl_add_u32 v50, v50, 4, v28
	v_lshl_add_u32 v51, v51, 4, v31
	v_lshl_add_u32 v24, v24, 4, v28
	v_lshl_add_u32 v25, v25, 4, v31
	v_bitop3_b32 v27, v33, v7, 6 bitop3:0x6c
	v_bitop3_b32 v28, v36, v7, 6 bitop3:0x6c
	v_bitop3_b32 v30, v39, v7, 7 bitop3:0x6c
	v_lshl_add_u32 v31, v6, 4, v42
	v_mad_i64_i32 v[6:7], s[12:13], v22, s14, 0
	v_and_b32_e32 v8, 0xf0, v8
	v_or_b32_e32 v6, v6, v8
	v_lshl_add_u64 v[82:83], v[6:7], 0, s[40:41]
	v_mad_i64_i32 v[6:7], s[12:13], v20, s14, 0
	v_or_b32_e32 v6, v6, v8
	v_lshl_add_u64 v[84:85], v[6:7], 0, s[40:41]
	v_mad_i64_i32 v[6:7], s[12:13], v18, s14, 0
	v_or_b32_e32 v6, v6, v8
	v_lshl_add_u64 v[86:87], v[6:7], 0, s[40:41]
	v_mad_i64_i32 v[6:7], s[12:13], v0, s14, 0
	v_lshlrev_b32_e32 v0, 7, v9
	v_or_b32_e32 v6, v6, v8
	v_lshl_or_b32 v0, v11, 15, v0
	v_lshl_add_u64 v[88:89], v[6:7], 0, s[40:41]
	v_and_or_b32 v6, v0, s42, v13
	s_waitcnt vmcnt(0)
	s_add_u32 s12, s0, s11
	v_or_b32_e32 v0, 0x4000, v6
	v_mov_b32_e32 v7, v1
	v_and_b32_e32 v14, 0x780, v14
	v_and_b32_e32 v23, 14, v23
	v_lshl_add_u32 v35, v35, 4, v34
	v_lshl_add_u32 v38, v38, 4, v37
	v_lshl_add_u32 v41, v41, 4, v40
	v_lshl_add_u32 v10, v10, 4, v42
	v_lshl_add_u32 v46, v46, 4, v34
	v_lshl_add_u32 v47, v47, 4, v37
	v_lshl_add_u32 v48, v48, 4, v40
	v_lshl_add_u32 v52, v52, 4, v34
	v_lshl_add_u32 v53, v53, 4, v37
	v_lshl_add_u32 v54, v54, 4, v40
	v_lshl_add_u32 v27, v27, 4, v34
	v_lshl_add_u32 v28, v28, 4, v37
	v_lshl_add_u32 v30, v30, 4, v40
	s_addc_u32 s13, s1, 0
	v_lshlrev_b64 v[8:9], 1, v[0:1]
	v_lshlrev_b64 v[6:7], 1, v[6:7]
	v_mov_b32_e32 v18, 0
	v_lshl_add_u64 v[90:91], s[12:13], 0, v[2:3]
	v_lshl_add_u64 v[92:93], s[12:13], 0, v[8:9]
	v_lshl_add_u64 v[94:95], s[12:13], 0, v[4:5]
	v_lshl_add_u64 v[96:97], s[12:13], 0, v[6:7]
	v_lshl_add_u64 v[98:99], s[38:39], 0, v[4:5]
	v_lshl_add_u64 v[100:101], s[38:39], 0, v[6:7]
	v_lshl_add_u64 v[102:103], s[38:39], 0, v[8:9]
	v_lshl_add_u64 v[104:105], s[38:39], 0, v[2:3]
	s_mov_b32 s11, 0
	v_add_u32_e32 v0, v15, v14
	v_add_u32_e32 v127, v17, v14
	v_add_u32_e32 v128, v12, v14
	v_add_u32_e32 v129, v16, v14
	v_add_u32_e32 v130, v26, v23
	v_add_u32_e32 v131, v29, v23
	v_add_u32_e32 v132, v32, v23
	v_add_u32_e32 v133, v35, v23
	v_add_u32_e32 v134, v38, v23
	v_add_u32_e32 v135, v41, v23
	v_add_u32_e32 v136, v10, v23
	v_add_u32_e32 v137, v43, v23
	v_add_u32_e32 v138, v44, v23
	v_add_u32_e32 v139, v45, v23
	v_add_u32_e32 v140, v46, v23
	v_add_u32_e32 v141, v47, v23
	v_add_u32_e32 v142, v48, v23
	v_add_u32_e32 v143, v49, v23
	v_add_u32_e32 v144, v19, v23
	v_add_u32_e32 v145, v50, v23
	v_add_u32_e32 v154, v51, v23
	v_add_u32_e32 v155, v52, v23
	v_add_u32_e32 v156, v53, v23
	v_add_u32_e32 v157, v54, v23
	v_add_u32_e32 v158, v55, v23
	v_add_u32_e32 v159, v21, v23
	v_add_u32_e32 v160, v24, v23
	v_add_u32_e32 v161, v25, v23
	v_add_u32_e32 v162, v27, v23
	v_add_u32_e32 v163, v28, v23
	v_add_u32_e32 v164, v30, v23
	v_add_u32_e32 v165, v31, v23
	v_and_b32_e32 v240, 15, v151
	v_lshrrev_b32_e32 v241, 4, v151
	v_sub_u32_e32 v242, v240, v241
	v_mul_i32_i24_e32 v244, 0xbff0, v242
	v_ashrrev_i32_e32 v245, 31, v244
	v_lshl_add_u64 v[82:83], v[82:83], 0, v[244:245]
	v_lshl_add_u64 v[84:85], v[84:85], 0, v[244:245]
	v_lshl_add_u64 v[86:87], v[86:87], 0, v[244:245]
	v_lshl_add_u64 v[88:89], v[88:89], 0, v[244:245]
	v_and_b32_e32 v246, 7, v240
	v_lshlrev_b32_e32 v246, 1, v246
	v_lshl_or_b32 v246, v241, 10, v246
	v_lshrrev_b32_e32 v247, 3, v240
	v_and_b32_e32 v242, 1, v241
	v_lshlrev_b32_e32 v242, 2, v242
	v_add_u32_e32 v243, 0, v247
	v_or_b32_e32 v248, 0, v242
	v_xor_b32_e32 v248, v243, v248
	v_lshl_add_u32 v130, v248, 4, v246
	v_or_b32_e32 v248, 1, v242
	v_xor_b32_e32 v248, v243, v248
	v_lshl_add_u32 v248, v248, 4, v246
	v_add_u32_e32 v131, 0x100, v248
	v_add_u32_e32 v132, 0x180, v248
	v_or_b32_e32 v248, 2, v242
	v_xor_b32_e32 v248, v243, v248
	v_lshl_add_u32 v248, v248, 4, v246
	v_add_u32_e32 v133, 0x200, v248
	v_add_u32_e32 v134, 0x280, v248
	v_or_b32_e32 v248, 3, v242
	v_xor_b32_e32 v248, v243, v248
	v_lshl_add_u32 v248, v248, 4, v246
	v_add_u32_e32 v135, 0x300, v248
	v_add_u32_e32 v136, 0x380, v248
	v_add_u32_e32 v243, 2, v247
	v_or_b32_e32 v248, 0, v242
	v_xor_b32_e32 v248, v243, v248
	v_lshl_add_u32 v137, v248, 4, v246
	v_or_b32_e32 v248, 1, v242
	v_xor_b32_e32 v248, v243, v248
	v_lshl_add_u32 v248, v248, 4, v246
	v_add_u32_e32 v138, 0x100, v248
	v_add_u32_e32 v139, 0x180, v248
	v_or_b32_e32 v248, 2, v242
	v_xor_b32_e32 v248, v243, v248
	v_lshl_add_u32 v248, v248, 4, v246
	v_add_u32_e32 v140, 0x200, v248
	v_add_u32_e32 v141, 0x280, v248
	v_or_b32_e32 v248, 3, v242
	v_xor_b32_e32 v248, v243, v248
	v_lshl_add_u32 v248, v248, 4, v246
	v_add_u32_e32 v142, 0x300, v248
	v_add_u32_e32 v143, 0x380, v248
	v_add_u32_e32 v243, 4, v247
	v_or_b32_e32 v248, 0, v242
	v_xor_b32_e32 v248, v243, v248
	v_lshl_add_u32 v144, v248, 4, v246
	v_or_b32_e32 v248, 1, v242
	v_xor_b32_e32 v248, v243, v248
	v_lshl_add_u32 v248, v248, 4, v246
	v_add_u32_e32 v145, 0x100, v248
	v_add_u32_e32 v154, 0x180, v248
	v_or_b32_e32 v248, 2, v242
	v_xor_b32_e32 v248, v243, v248
	v_lshl_add_u32 v248, v248, 4, v246
	v_add_u32_e32 v155, 0x200, v248
	v_add_u32_e32 v156, 0x280, v248
	v_or_b32_e32 v248, 3, v242
	v_xor_b32_e32 v248, v243, v248
	v_lshl_add_u32 v248, v248, 4, v246
	v_add_u32_e32 v157, 0x300, v248
	v_add_u32_e32 v158, 0x380, v248
	v_add_u32_e32 v243, 6, v247
	v_or_b32_e32 v248, 0, v242
	v_xor_b32_e32 v248, v243, v248
	v_lshl_add_u32 v159, v248, 4, v246
	v_or_b32_e32 v248, 1, v242
	v_xor_b32_e32 v248, v243, v248
	v_lshl_add_u32 v248, v248, 4, v246
	v_add_u32_e32 v160, 0x100, v248
	v_add_u32_e32 v161, 0x180, v248
	v_or_b32_e32 v248, 2, v242
	v_xor_b32_e32 v248, v243, v248
	v_lshl_add_u32 v248, v248, 4, v246
	v_add_u32_e32 v162, 0x200, v248
	v_add_u32_e32 v163, 0x280, v248
	v_or_b32_e32 v248, 3, v242
	v_xor_b32_e32 v248, v243, v248
	v_lshl_add_u32 v248, v248, 4, v246
	v_add_u32_e32 v164, 0x300, v248
	v_add_u32_e32 v165, 0x380, v248
	v_mov_b32_e32 v19, v18
	v_mov_b32_e32 v20, v18
	v_mov_b32_e32 v21, v18
	v_mov_b32_e32 v22, v18
	v_mov_b32_e32 v23, v18
	v_mov_b32_e32 v24, v18
	v_mov_b32_e32 v25, v18
	v_mov_b32_e32 v26, v18
	v_mov_b32_e32 v27, v18
	v_mov_b32_e32 v28, v18
	v_mov_b32_e32 v29, v18
	v_mov_b32_e32 v30, v18
	v_mov_b32_e32 v31, v18
	v_mov_b32_e32 v32, v18
	v_mov_b32_e32 v33, v18
	v_mov_b32_e32 v34, v18
	v_mov_b32_e32 v35, v18
	v_mov_b32_e32 v36, v18
	v_mov_b32_e32 v37, v18
	v_mov_b32_e32 v38, v18
	v_mov_b32_e32 v39, v18
	v_mov_b32_e32 v40, v18
	v_mov_b32_e32 v41, v18
	v_mov_b32_e32 v42, v18
	v_mov_b32_e32 v43, v18
	v_mov_b32_e32 v44, v18
	v_mov_b32_e32 v45, v18
	v_mov_b32_e32 v46, v18
	v_mov_b32_e32 v47, v18
	v_mov_b32_e32 v48, v18
	v_mov_b32_e32 v49, v18
	v_mov_b32_e32 v50, v18
	v_mov_b32_e32 v51, v18
	v_mov_b32_e32 v52, v18
	v_mov_b32_e32 v53, v18
	v_mov_b32_e32 v54, v18
	v_mov_b32_e32 v55, v18
	v_mov_b32_e32 v56, v18
	v_mov_b32_e32 v57, v18
	v_mov_b32_e32 v58, v18
	v_mov_b32_e32 v59, v18
	v_mov_b32_e32 v60, v18
	v_mov_b32_e32 v61, v18
	v_mov_b32_e32 v62, v18
	v_mov_b32_e32 v63, v18
	v_mov_b32_e32 v64, v18
	v_mov_b32_e32 v65, v18
	v_mov_b32_e32 v66, v18
	v_mov_b32_e32 v67, v18
	v_mov_b32_e32 v68, v18
	v_mov_b32_e32 v69, v18
	v_mov_b32_e32 v70, v18
	v_mov_b32_e32 v71, v18
	v_mov_b32_e32 v72, v18
	v_mov_b32_e32 v73, v18
	v_mov_b32_e32 v74, v18
	v_mov_b32_e32 v75, v18
	v_mov_b32_e32 v76, v18
	v_mov_b32_e32 v77, v18
	v_mov_b32_e32 v78, v18
	v_mov_b32_e32 v79, v18
	v_mov_b32_e32 v80, v18
	v_mov_b32_e32 v81, v18
	s_mov_b32 s13, 0x7b00000
	s_mov_b32 s17, 0x7e00000
	s_waitcnt lgkmcnt(0)
	s_barrier
	s_branch .LBB0_76
.LBB0_75:
	s_waitcnt vmcnt(0)
	v_lshl_add_u64 v[82:83], v[82:83], 0, s[20:21]
	v_lshl_add_u64 v[84:85], v[84:85], 0, s[20:21]
	v_lshl_add_u64 v[86:87], v[86:87], 0, s[20:21]
	v_lshl_add_u64 v[88:89], v[88:89], 0, s[20:21]
	s_andn2_b64 vcc, exec, s[38:39]
	s_mov_b32 s11, s12
	s_waitcnt vmcnt(0) lgkmcnt(0)
	s_barrier
	s_cbranch_vccz .LBB0_73
.LBB0_76:
	s_and_b32 s12, s11, 12
	s_cmp_eq_u32 s12, 8
	s_cselect_b64 s[38:39], -1, 0
	s_cmp_lg_u32 s12, 8
	s_mov_b64 s[40:41], -1
	s_cbranch_scc0 .LBB0_78
	v_readfirstlane_b32 s12, v122
	s_nop 0
	s_add_u32 m0, s12, 0x9000
	s_nop 0
	global_load_lds_dwordx4 v185, s[48:49]
	s_add_u32 m0, s12, 0xd000
	s_nop 0
	global_load_lds_dwordx4 v185, s[100:101]
	s_add_u32 m0, s12, 0x9400
	s_nop 0
	global_load_lds_dwordx4 v188, s[48:49]
	s_add_u32 m0, s12, 0xd400
	s_nop 0
	global_load_lds_dwordx4 v188, s[100:101]
	s_add_u32 m0, s12, 0x9800
	s_nop 0
	global_load_lds_dwordx4 v193, s[48:49]
	s_add_u32 m0, s12, 0xd800
	s_nop 0
	global_load_lds_dwordx4 v193, s[100:101]
	s_add_u32 m0, s12, 0x9c00
	s_nop 0
	global_load_lds_dwordx4 v194, s[48:49]
	s_add_u32 m0, s12, 0xdc00
	s_nop 0
	global_load_lds_dwordx4 v194, s[100:101]
	v_add_u32_e32 v185, 0x80, v185
	v_add_u32_e32 v188, 0x80, v188
	v_add_u32_e32 v193, 0x80, v193
	v_add_u32_e32 v194, 0x80, v194
	s_mov_b64 s[40:41], 0
.LBB0_78:
	s_andn2_b64 vcc, exec, s[40:41]
	s_cbranch_vccnz .LBB0_80
	v_readfirstlane_b32 s12, v122
	s_nop 0
	s_add_u32 m0, s12, 0xd000
	s_nop 0
	global_load_lds_dwordx4 v185, s[100:101]
	s_add_u32 m0, s12, 0xd400
	s_nop 0
	global_load_lds_dwordx4 v188, s[100:101]
	s_add_u32 m0, s12, 0xd800
	s_nop 0
	global_load_lds_dwordx4 v193, s[100:101]
	s_add_u32 m0, s12, 0xdc00
	s_nop 0
	global_load_lds_dwordx4 v194, s[100:101]
	v_add_u32_e32 v185, 0x80, v185
	v_add_u32_e32 v188, 0x80, v188
	v_add_u32_e32 v193, 0x80, v193
	v_add_u32_e32 v194, 0x80, v194
	v_lshl_add_u64 v[2:3], s[94:95], 0, v[88:89]
	v_add_co_u32_e32 v2, vcc, s13, v2
	v_lshl_add_u64 v[4:5], s[94:95], 0, v[86:87]
	s_nop 0
	v_addc_co_u32_e32 v3, vcc, 0, v3, vcc
	v_add_co_u32_e32 v6, vcc, s13, v4
	v_addc_co_u32_e32 v7, vcc, 0, v5, vcc
	v_lshl_add_u64 v[10:11], s[94:95], 0, v[84:85]
	v_add_co_u32_e32 v10, vcc, 0x7b00000, v10
	v_addc_co_u32_e32 v11, vcc, 0, v11, vcc
	v_lshl_add_u64 v[12:13], s[94:95], 0, v[82:83]
	v_add_co_u32_e32 v14, vcc, 0x7b00000, v12
	s_nop 0
	v_addc_co_u32_e32 v15, vcc, 0, v13, vcc
	global_load_dwordx4 v[2:5], v[2:3], off
	s_nop 0
	global_load_dwordx4 v[6:9], v[6:7], off
	s_nop 0
	global_load_dwordx4 v[10:13], v[10:11], off
	s_nop 0
	global_load_dwordx4 v[14:17], v[14:15], off

.LBB0_82:
	s_add_i32 s12, s11, 2
	s_waitcnt vmcnt(0)
	s_cmp_gt_u32 s11, 13
	s_cselect_b64 s[38:39], -1, 0
	s_mov_b64 s[40:41], 0
	s_and_b64 vcc, exec, s[38:39]
	s_waitcnt vmcnt(0) lgkmcnt(0)
	s_barrier
	s_cbranch_vccnz .LBB0_87
	s_and_b32 s11, s12, 28
	s_mov_b64 s[14:15], 0xe600100
	s_mov_b64 s[40:41], -1
	s_cmp_lg_u32 s11, 8
	s_cbranch_scc0 .LBB0_85
	v_readfirstlane_b32 s11, v122
	s_nop 0
	s_add_u32 m0, s11, 0x0
	s_nop 0
	global_load_lds_dwordx4 v185, s[48:49]
	s_add_u32 m0, s11, 0x4000
	s_nop 0
	global_load_lds_dwordx4 v185, s[100:101]
	s_add_u32 m0, s11, 0x400
	s_nop 0
	global_load_lds_dwordx4 v188, s[48:49]
	s_add_u32 m0, s11, 0x4400
	s_nop 0
	global_load_lds_dwordx4 v188, s[100:101]
	s_add_u32 m0, s11, 0x800
	s_nop 0
	global_load_lds_dwordx4 v193, s[48:49]
	s_add_u32 m0, s11, 0x4800
	s_nop 0
	global_load_lds_dwordx4 v193, s[100:101]
	s_add_u32 m0, s11, 0xc00
	s_nop 0
	global_load_lds_dwordx4 v194, s[48:49]
	s_add_u32 m0, s11, 0x4c00
	s_nop 0
	global_load_lds_dwordx4 v194, s[100:101]
	v_add_u32_e32 v185, 0x80, v185
	v_add_u32_e32 v188, 0x80, v188
	v_add_u32_e32 v193, 0x80, v193
	v_add_u32_e32 v194, 0x80, v194
	s_mov_b64 s[40:41], 0
.LBB0_85:
	s_andn2_b64 vcc, exec, s[40:41]
	s_mov_b64 s[40:41], 0
	s_cbranch_vccnz .LBB0_87
	v_readfirstlane_b32 s11, v122
	s_nop 0
	s_add_u32 m0, s11, 0x4000
	s_nop 0
	global_load_lds_dwordx4 v185, s[100:101]
	s_add_u32 m0, s11, 0x4400
	s_nop 0
	global_load_lds_dwordx4 v188, s[100:101]
	s_add_u32 m0, s11, 0x4800
	s_nop 0
	global_load_lds_dwordx4 v193, s[100:101]
	s_add_u32 m0, s11, 0x4c00
	s_nop 0
	global_load_lds_dwordx4 v194, s[100:101]
	v_add_u32_e32 v185, 0x80, v185
	v_add_u32_e32 v188, 0x80, v188
	v_add_u32_e32 v193, 0x80, v193
	v_add_u32_e32 v194, 0x80, v194
	v_lshl_add_u64 v[2:3], s[94:95], 0, v[88:89]
	v_add_co_u32_e32 v2, vcc, s17, v2
	v_lshl_add_u64 v[4:5], s[94:95], 0, v[86:87]
	s_nop 0
	v_addc_co_u32_e32 v3, vcc, 0, v3, vcc
	v_add_co_u32_e32 v6, vcc, s17, v4
	v_addc_co_u32_e32 v7, vcc, 0, v5, vcc
	v_lshl_add_u64 v[10:11], s[94:95], 0, v[84:85]
	v_add_co_u32_e32 v10, vcc, 0x7e00000, v10
	v_addc_co_u32_e32 v11, vcc, 0, v11, vcc
	v_lshl_add_u64 v[12:13], s[94:95], 0, v[82:83]
	v_add_co_u32_e32 v14, vcc, 0x7e00000, v12
	s_nop 0
	v_addc_co_u32_e32 v15, vcc, 0, v13, vcc
	global_load_dwordx4 v[2:5], v[2:3], off
	s_nop 0
	global_load_dwordx4 v[6:9], v[6:7], off
	s_nop 0
	global_load_dwordx4 v[10:13], v[10:11], off
	s_nop 0
	global_load_dwordx4 v[14:17], v[14:15], off
	s_mov_b64 s[40:41], -1
